# adds: P11 residual epilogue hand-written with all 24 loads in flight and counted waits
# baseline (speedup 1.0000x reference)
.LBB0_809:
	s_and_b64 vcc, exec, s[0:1]
	s_mov_b64 s[0:1], -1
	s_ashr_i32 s26, s51, 31
	s_lshr_b32 s26, s26, 27
	s_add_i32 s26, s51, s26
	s_ashr_i32 s26, s26, 5
	s_mul_hi_i32 s27, s26, 0x6000
	s_mulk_i32 s26, 0x6000
	s_add_u32 s26, s42, s26
	s_addc_u32 s27, s43, s27
	v_lshl_add_u32 v156, s51, 8, v158
	v_lshl_or_b32 v252, s52, 8, v160
	v_lshlrev_b32_e32 v156, 11, v156
	v_lshl_add_u32 v156, v252, 1, v156
	v_lshlrev_b32_e32 v157, 1, v156
	v_lshlrev_b32_e32 v252, 2, v252
	global_load_dwordx4 v[228:231], v252, s[26:27]
	global_load_dwordx4 v[232:235], v252, s[26:27] offset:16
	global_load_dwordx4 v[236:239], v252, s[26:27] offset:512
	global_load_dwordx4 v[240:243], v252, s[26:27] offset:528
	global_load_dwordx4 v[244:247], v252, s[8:9]
	global_load_dwordx4 v[248:251], v252, s[8:9] offset:16
	global_load_dwordx4 v[144:147], v252, s[8:9] offset:512
	global_load_dwordx4 v[148:151], v252, s[8:9] offset:528
	s_mov_b32 s16, s14
	s_mov_b32 s17, s15
	global_load_dwordx4 v[164:167], v156, s[16:17] nt
	global_load_dwordx4 v[168:171], v156, s[16:17] offset:256 nt
	s_add_u32 s16, s16, 0x8000
	s_addc_u32 s17, s17, 0
	global_load_dwordx4 v[172:175], v156, s[16:17] nt
	global_load_dwordx4 v[176:179], v156, s[16:17] offset:256 nt
	s_add_u32 s16, s16, 0x8000
	s_addc_u32 s17, s17, 0
	global_load_dwordx4 v[180:183], v156, s[16:17] nt
	global_load_dwordx4 v[184:187], v156, s[16:17] offset:256 nt
	s_add_u32 s16, s16, 0x8000
	s_addc_u32 s17, s17, 0
	global_load_dwordx4 v[188:191], v156, s[16:17] nt
	global_load_dwordx4 v[192:195], v156, s[16:17] offset:256 nt
	s_add_u32 s16, s16, 0x28000
	s_addc_u32 s17, s17, 0
	global_load_dwordx4 v[196:199], v156, s[16:17] nt
	global_load_dwordx4 v[200:203], v156, s[16:17] offset:256 nt
	s_add_u32 s16, s16, 0x8000
	s_addc_u32 s17, s17, 0
	global_load_dwordx4 v[204:207], v156, s[16:17] nt
	global_load_dwordx4 v[208:211], v156, s[16:17] offset:256 nt
	s_add_u32 s16, s16, 0x8000
	s_addc_u32 s17, s17, 0
	global_load_dwordx4 v[212:215], v156, s[16:17] nt
	global_load_dwordx4 v[216:219], v156, s[16:17] offset:256 nt
	s_add_u32 s16, s16, 0x8000
	s_addc_u32 s17, s17, 0
	global_load_dwordx4 v[220:223], v156, s[16:17] nt
	global_load_dwordx4 v[224:227], v156, s[16:17] offset:256 nt
	s_mov_b32 s18, s86
	s_mov_b32 s19, s87
	s_waitcnt vmcnt(16)
	v_pk_add_f32 v[228:229], v[228:229], v[244:245]
	v_pk_add_f32 v[230:231], v[230:231], v[246:247]
	v_pk_add_f32 v[232:233], v[232:233], v[248:249]
	v_pk_add_f32 v[234:235], v[234:235], v[250:251]
	v_pk_add_f32 v[236:237], v[236:237], v[144:145]
	v_pk_add_f32 v[238:239], v[238:239], v[146:147]
	v_pk_add_f32 v[240:241], v[240:241], v[148:149]
	v_pk_add_f32 v[242:243], v[242:243], v[150:151]
	s_waitcnt vmcnt(15)
	v_lshlrev_b32_e32 v152, 16, v164
	v_and_b32_e32 v153, 0xffff0000, v164
	v_pk_fma_f32 v[124:125], v[124:125], v[228:229], v[152:153]
	v_lshlrev_b32_e32 v154, 16, v165
	v_and_b32_e32 v155, 0xffff0000, v165
	v_pk_fma_f32 v[126:127], v[126:127], v[230:231], v[154:155]
	v_lshlrev_b32_e32 v152, 16, v166
	v_and_b32_e32 v153, 0xffff0000, v166
	v_pk_fma_f32 v[120:121], v[120:121], v[232:233], v[152:153]
	v_lshlrev_b32_e32 v154, 16, v167
	v_and_b32_e32 v155, 0xffff0000, v167
	v_pk_fma_f32 v[122:123], v[122:123], v[234:235], v[154:155]
	global_store_dwordx4 v157, v[124:127], s[18:19] nt
	global_store_dwordx4 v157, v[120:123], s[18:19] offset:16 nt
	s_waitcnt vmcnt(16)
	v_lshlrev_b32_e32 v152, 16, v168
	v_and_b32_e32 v153, 0xffff0000, v168
	v_pk_fma_f32 v[116:117], v[116:117], v[236:237], v[152:153]
	v_lshlrev_b32_e32 v154, 16, v169
	v_and_b32_e32 v155, 0xffff0000, v169
	v_pk_fma_f32 v[118:119], v[118:119], v[238:239], v[154:155]
	v_lshlrev_b32_e32 v152, 16, v170
	v_and_b32_e32 v153, 0xffff0000, v170
	v_pk_fma_f32 v[112:113], v[112:113], v[240:241], v[152:153]
	v_lshlrev_b32_e32 v154, 16, v171
	v_and_b32_e32 v155, 0xffff0000, v171
	v_pk_fma_f32 v[114:115], v[114:115], v[242:243], v[154:155]
	global_store_dwordx4 v157, v[116:119], s[18:19] offset:512 nt
	global_store_dwordx4 v157, v[112:115], s[18:19] offset:528 nt
	s_add_u32 s18, s18, 0x10000
	s_addc_u32 s19, s19, 0
	s_waitcnt vmcnt(17)
	v_lshlrev_b32_e32 v152, 16, v172
	v_and_b32_e32 v153, 0xffff0000, v172
	v_pk_fma_f32 v[108:109], v[108:109], v[228:229], v[152:153]
	v_lshlrev_b32_e32 v154, 16, v173
	v_and_b32_e32 v155, 0xffff0000, v173
	v_pk_fma_f32 v[110:111], v[110:111], v[230:231], v[154:155]
	v_lshlrev_b32_e32 v152, 16, v174
	v_and_b32_e32 v153, 0xffff0000, v174
	v_pk_fma_f32 v[104:105], v[104:105], v[232:233], v[152:153]
	v_lshlrev_b32_e32 v154, 16, v175
	v_and_b32_e32 v155, 0xffff0000, v175
	v_pk_fma_f32 v[106:107], v[106:107], v[234:235], v[154:155]
	global_store_dwordx4 v157, v[108:111], s[18:19] nt
	global_store_dwordx4 v157, v[104:107], s[18:19] offset:16 nt
	s_waitcnt vmcnt(18)
	v_lshlrev_b32_e32 v152, 16, v176
	v_and_b32_e32 v153, 0xffff0000, v176
	v_pk_fma_f32 v[100:101], v[100:101], v[236:237], v[152:153]
	v_lshlrev_b32_e32 v154, 16, v177
	v_and_b32_e32 v155, 0xffff0000, v177
	v_pk_fma_f32 v[102:103], v[102:103], v[238:239], v[154:155]
	v_lshlrev_b32_e32 v152, 16, v178
	v_and_b32_e32 v153, 0xffff0000, v178
	v_pk_fma_f32 v[96:97], v[96:97], v[240:241], v[152:153]
	v_lshlrev_b32_e32 v154, 16, v179
	v_and_b32_e32 v155, 0xffff0000, v179
	v_pk_fma_f32 v[98:99], v[98:99], v[242:243], v[154:155]
	global_store_dwordx4 v157, v[100:103], s[18:19] offset:512 nt
	global_store_dwordx4 v157, v[96:99], s[18:19] offset:528 nt
	s_add_u32 s18, s18, 0x10000
	s_addc_u32 s19, s19, 0
	s_waitcnt vmcnt(19)
	v_lshlrev_b32_e32 v152, 16, v180
	v_and_b32_e32 v153, 0xffff0000, v180
	v_pk_fma_f32 v[92:93], v[92:93], v[228:229], v[152:153]
	v_lshlrev_b32_e32 v154, 16, v181
	v_and_b32_e32 v155, 0xffff0000, v181
	v_pk_fma_f32 v[94:95], v[94:95], v[230:231], v[154:155]
	v_lshlrev_b32_e32 v152, 16, v182
	v_and_b32_e32 v153, 0xffff0000, v182
	v_pk_fma_f32 v[88:89], v[88:89], v[232:233], v[152:153]
	v_lshlrev_b32_e32 v154, 16, v183
	v_and_b32_e32 v155, 0xffff0000, v183
	v_pk_fma_f32 v[90:91], v[90:91], v[234:235], v[154:155]
	global_store_dwordx4 v157, v[92:95], s[18:19] nt
	global_store_dwordx4 v157, v[88:91], s[18:19] offset:16 nt
	s_waitcnt vmcnt(20)
	v_lshlrev_b32_e32 v152, 16, v184
	v_and_b32_e32 v153, 0xffff0000, v184
	v_pk_fma_f32 v[84:85], v[84:85], v[236:237], v[152:153]
	v_lshlrev_b32_e32 v154, 16, v185
	v_and_b32_e32 v155, 0xffff0000, v185
	v_pk_fma_f32 v[86:87], v[86:87], v[238:239], v[154:155]
	v_lshlrev_b32_e32 v152, 16, v186
	v_and_b32_e32 v153, 0xffff0000, v186
	v_pk_fma_f32 v[80:81], v[80:81], v[240:241], v[152:153]
	v_lshlrev_b32_e32 v154, 16, v187
	v_and_b32_e32 v155, 0xffff0000, v187
	v_pk_fma_f32 v[82:83], v[82:83], v[242:243], v[154:155]
	global_store_dwordx4 v157, v[84:87], s[18:19] offset:512 nt
	global_store_dwordx4 v157, v[80:83], s[18:19] offset:528 nt
	s_add_u32 s18, s18, 0x10000
	s_addc_u32 s19, s19, 0
	s_waitcnt vmcnt(21)
	v_lshlrev_b32_e32 v152, 16, v188
	v_and_b32_e32 v153, 0xffff0000, v188
	v_pk_fma_f32 v[76:77], v[76:77], v[228:229], v[152:153]
	v_lshlrev_b32_e32 v154, 16, v189
	v_and_b32_e32 v155, 0xffff0000, v189
	v_pk_fma_f32 v[78:79], v[78:79], v[230:231], v[154:155]
	v_lshlrev_b32_e32 v152, 16, v190
	v_and_b32_e32 v153, 0xffff0000, v190
	v_pk_fma_f32 v[72:73], v[72:73], v[232:233], v[152:153]
	v_lshlrev_b32_e32 v154, 16, v191
	v_and_b32_e32 v155, 0xffff0000, v191
	v_pk_fma_f32 v[74:75], v[74:75], v[234:235], v[154:155]
	global_store_dwordx4 v157, v[76:79], s[18:19] nt
	global_store_dwordx4 v157, v[72:75], s[18:19] offset:16 nt
	s_waitcnt vmcnt(22)
	v_lshlrev_b32_e32 v152, 16, v192
	v_and_b32_e32 v153, 0xffff0000, v192
	v_pk_fma_f32 v[68:69], v[68:69], v[236:237], v[152:153]
	v_lshlrev_b32_e32 v154, 16, v193
	v_and_b32_e32 v155, 0xffff0000, v193
	v_pk_fma_f32 v[70:71], v[70:71], v[238:239], v[154:155]
	v_lshlrev_b32_e32 v152, 16, v194
	v_and_b32_e32 v153, 0xffff0000, v194
	v_pk_fma_f32 v[64:65], v[64:65], v[240:241], v[152:153]
	v_lshlrev_b32_e32 v154, 16, v195
	v_and_b32_e32 v155, 0xffff0000, v195
	v_pk_fma_f32 v[66:67], v[66:67], v[242:243], v[154:155]
	global_store_dwordx4 v157, v[68:71], s[18:19] offset:512 nt
	global_store_dwordx4 v157, v[64:67], s[18:19] offset:528 nt
	s_add_u32 s18, s18, 0x50000
	s_addc_u32 s19, s19, 0
	s_waitcnt vmcnt(23)
	v_lshlrev_b32_e32 v152, 16, v196
	v_and_b32_e32 v153, 0xffff0000, v196
	v_pk_fma_f32 v[60:61], v[60:61], v[228:229], v[152:153]
	v_lshlrev_b32_e32 v154, 16, v197
	v_and_b32_e32 v155, 0xffff0000, v197
	v_pk_fma_f32 v[62:63], v[62:63], v[230:231], v[154:155]
	v_lshlrev_b32_e32 v152, 16, v198
	v_and_b32_e32 v153, 0xffff0000, v198
	v_pk_fma_f32 v[56:57], v[56:57], v[232:233], v[152:153]
	v_lshlrev_b32_e32 v154, 16, v199
	v_and_b32_e32 v155, 0xffff0000, v199
	v_pk_fma_f32 v[58:59], v[58:59], v[234:235], v[154:155]
	global_store_dwordx4 v157, v[60:63], s[18:19] nt
	global_store_dwordx4 v157, v[56:59], s[18:19] offset:16 nt
	s_waitcnt vmcnt(24)
	v_lshlrev_b32_e32 v152, 16, v200
	v_and_b32_e32 v153, 0xffff0000, v200
	v_pk_fma_f32 v[52:53], v[52:53], v[236:237], v[152:153]
	v_lshlrev_b32_e32 v154, 16, v201
	v_and_b32_e32 v155, 0xffff0000, v201
	v_pk_fma_f32 v[54:55], v[54:55], v[238:239], v[154:155]
	v_lshlrev_b32_e32 v152, 16, v202
	v_and_b32_e32 v153, 0xffff0000, v202
	v_pk_fma_f32 v[48:49], v[48:49], v[240:241], v[152:153]
	v_lshlrev_b32_e32 v154, 16, v203
	v_and_b32_e32 v155, 0xffff0000, v203
	v_pk_fma_f32 v[50:51], v[50:51], v[242:243], v[154:155]
	global_store_dwordx4 v157, v[52:55], s[18:19] offset:512 nt
	global_store_dwordx4 v157, v[48:51], s[18:19] offset:528 nt
	s_add_u32 s18, s18, 0x10000
	s_addc_u32 s19, s19, 0
	s_waitcnt vmcnt(25)
	v_lshlrev_b32_e32 v152, 16, v204
	v_and_b32_e32 v153, 0xffff0000, v204
	v_pk_fma_f32 v[44:45], v[44:45], v[228:229], v[152:153]
	v_lshlrev_b32_e32 v154, 16, v205
	v_and_b32_e32 v155, 0xffff0000, v205
	v_pk_fma_f32 v[46:47], v[46:47], v[230:231], v[154:155]
	v_lshlrev_b32_e32 v152, 16, v206
	v_and_b32_e32 v153, 0xffff0000, v206
	v_pk_fma_f32 v[40:41], v[40:41], v[232:233], v[152:153]
	v_lshlrev_b32_e32 v154, 16, v207
	v_and_b32_e32 v155, 0xffff0000, v207
	v_pk_fma_f32 v[42:43], v[42:43], v[234:235], v[154:155]
	global_store_dwordx4 v157, v[44:47], s[18:19] nt
	global_store_dwordx4 v157, v[40:43], s[18:19] offset:16 nt
	s_waitcnt vmcnt(26)
	v_lshlrev_b32_e32 v152, 16, v208
	v_and_b32_e32 v153, 0xffff0000, v208
	v_pk_fma_f32 v[36:37], v[36:37], v[236:237], v[152:153]
	v_lshlrev_b32_e32 v154, 16, v209
	v_and_b32_e32 v155, 0xffff0000, v209
	v_pk_fma_f32 v[38:39], v[38:39], v[238:239], v[154:155]
	v_lshlrev_b32_e32 v152, 16, v210
	v_and_b32_e32 v153, 0xffff0000, v210
	v_pk_fma_f32 v[32:33], v[32:33], v[240:241], v[152:153]
	v_lshlrev_b32_e32 v154, 16, v211
	v_and_b32_e32 v155, 0xffff0000, v211
	v_pk_fma_f32 v[34:35], v[34:35], v[242:243], v[154:155]
	global_store_dwordx4 v157, v[36:39], s[18:19] offset:512 nt
	global_store_dwordx4 v157, v[32:35], s[18:19] offset:528 nt
	s_add_u32 s18, s18, 0x10000
	s_addc_u32 s19, s19, 0
	s_waitcnt vmcnt(27)
	v_lshlrev_b32_e32 v152, 16, v212
	v_and_b32_e32 v153, 0xffff0000, v212
	v_pk_fma_f32 v[28:29], v[28:29], v[228:229], v[152:153]
	v_lshlrev_b32_e32 v154, 16, v213
	v_and_b32_e32 v155, 0xffff0000, v213
	v_pk_fma_f32 v[30:31], v[30:31], v[230:231], v[154:155]
	v_lshlrev_b32_e32 v152, 16, v214
	v_and_b32_e32 v153, 0xffff0000, v214
	v_pk_fma_f32 v[24:25], v[24:25], v[232:233], v[152:153]
	v_lshlrev_b32_e32 v154, 16, v215
	v_and_b32_e32 v155, 0xffff0000, v215
	v_pk_fma_f32 v[26:27], v[26:27], v[234:235], v[154:155]
	global_store_dwordx4 v157, v[28:31], s[18:19] nt
	global_store_dwordx4 v157, v[24:27], s[18:19] offset:16 nt
	s_waitcnt vmcnt(28)
	v_lshlrev_b32_e32 v152, 16, v216
	v_and_b32_e32 v153, 0xffff0000, v216
	v_pk_fma_f32 v[20:21], v[20:21], v[236:237], v[152:153]
	v_lshlrev_b32_e32 v154, 16, v217
	v_and_b32_e32 v155, 0xffff0000, v217
	v_pk_fma_f32 v[22:23], v[22:23], v[238:239], v[154:155]
	v_lshlrev_b32_e32 v152, 16, v218
	v_and_b32_e32 v153, 0xffff0000, v218
	v_pk_fma_f32 v[16:17], v[16:17], v[240:241], v[152:153]
	v_lshlrev_b32_e32 v154, 16, v219
	v_and_b32_e32 v155, 0xffff0000, v219
	v_pk_fma_f32 v[18:19], v[18:19], v[242:243], v[154:155]
	global_store_dwordx4 v157, v[20:23], s[18:19] offset:512 nt
	global_store_dwordx4 v157, v[16:19], s[18:19] offset:528 nt
	s_add_u32 s18, s18, 0x10000
	s_addc_u32 s19, s19, 0
	s_waitcnt vmcnt(29)
	v_lshlrev_b32_e32 v152, 16, v220
	v_and_b32_e32 v153, 0xffff0000, v220
	v_pk_fma_f32 v[12:13], v[12:13], v[228:229], v[152:153]
	v_lshlrev_b32_e32 v154, 16, v221
	v_and_b32_e32 v155, 0xffff0000, v221
	v_pk_fma_f32 v[14:15], v[14:15], v[230:231], v[154:155]
	v_lshlrev_b32_e32 v152, 16, v222
	v_and_b32_e32 v153, 0xffff0000, v222
	v_pk_fma_f32 v[8:9], v[8:9], v[232:233], v[152:153]
	v_lshlrev_b32_e32 v154, 16, v223
	v_and_b32_e32 v155, 0xffff0000, v223
	v_pk_fma_f32 v[10:11], v[10:11], v[234:235], v[154:155]
	global_store_dwordx4 v157, v[12:15], s[18:19] nt
	global_store_dwordx4 v157, v[8:11], s[18:19] offset:16 nt
	s_waitcnt vmcnt(30)
	v_lshlrev_b32_e32 v152, 16, v224
	v_and_b32_e32 v153, 0xffff0000, v224
	v_pk_fma_f32 v[4:5], v[4:5], v[236:237], v[152:153]
	v_lshlrev_b32_e32 v154, 16, v225
	v_and_b32_e32 v155, 0xffff0000, v225
	v_pk_fma_f32 v[6:7], v[6:7], v[238:239], v[154:155]
	v_lshlrev_b32_e32 v152, 16, v226
	v_and_b32_e32 v153, 0xffff0000, v226
	v_pk_fma_f32 v[0:1], v[0:1], v[240:241], v[152:153]
	v_lshlrev_b32_e32 v154, 16, v227
	v_and_b32_e32 v155, 0xffff0000, v227
	v_pk_fma_f32 v[2:3], v[2:3], v[242:243], v[154:155]
	global_store_dwordx4 v157, v[4:7], s[18:19] offset:512 nt
	global_store_dwordx4 v157, v[0:3], s[18:19] offset:528 nt
	s_cbranch_vccnz .LBB0_794
	s_andn2_b64 vcc, exec, s[6:7]
	s_cbranch_vccnz .LBB0_793
	s_barrier
	s_branch .LBB0_793
